# FFN-in tile loop: drop the header vmcnt(0) that only waited for the previous tile's epilogue stores (kept on first-tile entry)
# baseline (speedup 1.0000x reference)
.LBB0_160:
	s_add_u32 s0, s66, 0x60c0000
	s_addc_u32 s1, s67, 0
	s_add_u32 s28, s66, 0x6442000
	s_addc_u32 s29, s67, 0
	s_ashr_i32 s6, s3, 31
	s_lshr_b32 s6, s6, 26
	s_lshl_b32 s4, s4, 5
	s_add_i32 s6, s3, s6
	s_and_b32 s34, s4, 0x60
	s_add_i32 m0, s13, 0x18000
	v_lshl_add_u64 v[8:9], v[8:9], 0, s[84:85]
	s_ashr_i32 s30, s6, 6
	s_lshl_b32 s31, s5, 6
	s_lshl_b32 s6, s5, 13
	s_lshl_b32 s7, s34, 7
	s_waitcnt vmcnt(4)
	s_barrier
	global_load_lds_dwordx4 v[8:9], off
	v_lshl_add_u64 v[6:7], v[6:7], 0, s[84:85]
	s_add_i32 m0, s13, 0x1a000
	s_add_i32 s35, s13, 0x8000
	s_add_i32 s38, s13, 0xa000
	global_load_lds_dwordx4 v[6:7], off
	v_lshl_add_u64 v[4:5], v[4:5], 0, s[84:85]
	s_mov_b32 m0, s35
	s_add_u32 s4, s16, 0x40080
	global_load_lds_dwordx4 v[4:5], off
	v_lshl_add_u64 v[2:3], v[2:3], 0, s[84:85]
	s_mov_b32 m0, s38
	s_addc_u32 s5, s17, 0
	global_load_lds_dwordx4 v[2:3], off
	s_add_i32 m0, s13, 0x1c000
	v_lshl_add_u64 v[2:3], s[4:5], 0, v[150:151]
	global_load_lds_dwordx4 v[2:3], off
	v_lshl_add_u64 v[2:3], s[4:5], 0, v[146:147]
	s_add_i32 m0, s13, 0x1e000
	v_bfe_u32 v1, v170, 4, 2
	global_load_lds_dwordx4 v[2:3], off
	v_and_b32_e32 v159, 15, v170
	v_lshlrev_b32_e32 v2, 4, v1
	v_lshlrev_b32_e32 v3, 2, v170
	v_lshl_or_b32 v2, v159, 6, v2
	v_and_b32_e32 v3, 32, v3
	v_bitop3_b32 v4, v2, s6, v3 bitop3:0xde
	v_bitop3_b32 v171, s7, v2, v3 bitop3:0xf6
	v_lshlrev_b32_e32 v2, 14, v14
	v_and_b32_e32 v2, 0xffff8000, v2
	v_lshl_add_u32 v2, v13, 11, v2
	v_and_b32_e32 v3, 1, v14
	v_lshl_or_b32 v2, v3, 6, v2
	v_lshl_add_u32 v154, v15, 1, v2
	v_lshlrev_b32_e32 v2, 14, v10
	v_and_b32_e32 v2, 0xffff8000, v2
	s_waitcnt vmcnt(6)
	v_lshl_add_u32 v2, v11, 11, v2
	v_and_b32_e32 v3, 1, v10
	s_cmp_gt_i32 s3, 63
	v_lshl_or_b32 v2, v3, 6, v2
	s_sext_i32_i16 s42, s2
	s_cselect_b64 s[2:3], -1, 0
	s_add_i32 s39, s30, -2
	s_ashr_i32 s40, s83, 31
	v_mov_b32_e32 v155, v0
	v_lshl_add_u32 v156, v12, 1, v2
	v_mov_b32_e32 v157, v0
	s_mov_b32 s41, 0
	v_add_u32_e32 v173, 0, v4
	s_barrier
	s_waitcnt vmcnt(0)
	s_branch .LBB0_162

.LBB0_164:
	s_ashr_i32 s7, s6, 31
	s_lshl_b64 s[8:9], s[6:7], 19
	s_add_u32 s8, s64, s8
	s_addc_u32 s9, s65, s9
	s_ashr_i32 s5, s4, 31
	s_lshl_b64 s[10:11], s[4:5], 19
	s_add_u32 s10, s21, s10
	v_mov_b32_e32 v141, 0
	s_addc_u32 s11, s22, s11
	s_andn2_b64 vcc, exec, s[2:3]
	v_mov_b32_e32 v140, v141
	v_mov_b32_e32 v139, v141
	v_mov_b32_e32 v138, v141
	v_mov_b32_e32 v137, v141
	v_mov_b32_e32 v136, v141
	v_mov_b32_e32 v135, v141
	v_mov_b32_e32 v134, v141
	v_mov_b32_e32 v129, v141
	v_mov_b32_e32 v128, v141
	v_mov_b32_e32 v127, v141
	v_mov_b32_e32 v126, v141
	v_mov_b32_e32 v121, v141
	v_mov_b32_e32 v120, v141
	v_mov_b32_e32 v119, v141
	v_mov_b32_e32 v118, v141
	v_mov_b32_e32 v113, v141
	v_mov_b32_e32 v112, v141
	v_mov_b32_e32 v111, v141
	v_mov_b32_e32 v110, v141
	v_mov_b32_e32 v97, v141
	v_mov_b32_e32 v96, v141
	v_mov_b32_e32 v95, v141
	v_mov_b32_e32 v94, v141
	v_mov_b32_e32 v81, v141
	v_mov_b32_e32 v80, v141
	v_mov_b32_e32 v79, v141
	v_mov_b32_e32 v78, v141
	v_mov_b32_e32 v73, v141
	v_mov_b32_e32 v72, v141
	v_mov_b32_e32 v71, v141
	v_mov_b32_e32 v70, v141
	v_mov_b32_e32 v145, v141
	v_mov_b32_e32 v144, v141
	v_mov_b32_e32 v143, v141
	v_mov_b32_e32 v142, v141
	v_mov_b32_e32 v133, v141
	v_mov_b32_e32 v132, v141
	v_mov_b32_e32 v131, v141
	v_mov_b32_e32 v130, v141
	v_mov_b32_e32 v125, v141
	v_mov_b32_e32 v124, v141
	v_mov_b32_e32 v123, v141
	v_mov_b32_e32 v122, v141
	v_mov_b32_e32 v117, v141
	v_mov_b32_e32 v116, v141
	v_mov_b32_e32 v115, v141
	v_mov_b32_e32 v114, v141
	v_mov_b32_e32 v109, v141
	v_mov_b32_e32 v108, v141
	v_mov_b32_e32 v107, v141
	v_mov_b32_e32 v106, v141
	v_mov_b32_e32 v93, v141
	v_mov_b32_e32 v92, v141
	v_mov_b32_e32 v91, v141
	v_mov_b32_e32 v90, v141
	v_mov_b32_e32 v77, v141
	v_mov_b32_e32 v76, v141
	v_mov_b32_e32 v75, v141
	v_mov_b32_e32 v74, v141
	v_mov_b32_e32 v69, v141
	v_mov_b32_e32 v68, v141
	v_mov_b32_e32 v67, v141
	v_mov_b32_e32 v66, v141
	v_mov_b32_e32 v65, v141
	v_mov_b32_e32 v64, v141
	v_mov_b32_e32 v63, v141
	v_mov_b32_e32 v62, v141
	v_mov_b32_e32 v57, v141
	v_mov_b32_e32 v56, v141
	v_mov_b32_e32 v55, v141
	v_mov_b32_e32 v54, v141
	v_mov_b32_e32 v49, v141
	v_mov_b32_e32 v48, v141
	v_mov_b32_e32 v47, v141
	v_mov_b32_e32 v46, v141
	v_mov_b32_e32 v41, v141
	v_mov_b32_e32 v40, v141
	v_mov_b32_e32 v39, v141
	v_mov_b32_e32 v38, v141
	v_mov_b32_e32 v33, v141
	v_mov_b32_e32 v32, v141
	v_mov_b32_e32 v31, v141
	v_mov_b32_e32 v30, v141
	v_mov_b32_e32 v25, v141
	v_mov_b32_e32 v24, v141
	v_mov_b32_e32 v23, v141
	v_mov_b32_e32 v22, v141
	v_mov_b32_e32 v17, v141
	v_mov_b32_e32 v16, v141
	v_mov_b32_e32 v15, v141
	v_mov_b32_e32 v14, v141
	v_mov_b32_e32 v9, v141
	v_mov_b32_e32 v8, v141
	v_mov_b32_e32 v7, v141
	v_mov_b32_e32 v6, v141
	v_mov_b32_e32 v61, v141
	v_mov_b32_e32 v60, v141
	v_mov_b32_e32 v59, v141
	v_mov_b32_e32 v58, v141
	v_mov_b32_e32 v53, v141
	v_mov_b32_e32 v52, v141
	v_mov_b32_e32 v51, v141
	v_mov_b32_e32 v50, v141
	v_mov_b32_e32 v45, v141
	v_mov_b32_e32 v44, v141
	v_mov_b32_e32 v43, v141
	v_mov_b32_e32 v42, v141
	v_mov_b32_e32 v37, v141
	v_mov_b32_e32 v36, v141
	v_mov_b32_e32 v35, v141
	v_mov_b32_e32 v34, v141
	v_mov_b32_e32 v29, v141
	v_mov_b32_e32 v28, v141
	v_mov_b32_e32 v27, v141
	v_mov_b32_e32 v26, v141
	v_mov_b32_e32 v21, v141
	v_mov_b32_e32 v20, v141
	v_mov_b32_e32 v19, v141
	v_mov_b32_e32 v18, v141
	v_mov_b32_e32 v13, v141
	v_mov_b32_e32 v12, v141
	v_mov_b32_e32 v11, v141
	v_mov_b32_e32 v10, v141
	v_mov_b32_e32 v5, v141
	v_mov_b32_e32 v4, v141
	v_mov_b32_e32 v3, v141
	v_mov_b32_e32 v2, v141
	s_cbranch_vccnz .LBB0_161
	v_mov_b64_e32 v[2:3], 0xb00
	v_cmp_lt_i64_e32 vcc, s[18:19], v[2:3]
	s_and_b64 s[18:19], vcc, exec
	s_cselect_b32 s5, s9, s15
	s_cselect_b32 s7, s8, s14
	s_cselect_b32 s43, s11, s17
	s_cselect_b32 s44, s10, s16
	s_add_u32 s14, s14, 0x40080
	s_addc_u32 s15, s15, 0
	s_add_u32 s45, s16, 0x100
	v_mov_b32_e32 v2, 0
	s_addc_u32 s46, s17, 0
	s_mov_b32 s16, 0
	v_mov_b32_e32 v3, v2
	v_mov_b32_e32 v4, v2
	v_mov_b32_e32 v5, v2
	v_mov_b32_e32 v10, v2
	v_mov_b32_e32 v11, v2
	v_mov_b32_e32 v12, v2
	v_mov_b32_e32 v13, v2
	v_mov_b32_e32 v18, v2
	v_mov_b32_e32 v19, v2
	v_mov_b32_e32 v20, v2
	v_mov_b32_e32 v21, v2
	v_mov_b32_e32 v26, v2
	v_mov_b32_e32 v27, v2
	v_mov_b32_e32 v28, v2
	v_mov_b32_e32 v29, v2
	v_mov_b32_e32 v34, v2
	v_mov_b32_e32 v35, v2
	v_mov_b32_e32 v36, v2
	v_mov_b32_e32 v37, v2
	v_mov_b32_e32 v42, v2
	v_mov_b32_e32 v43, v2
	v_mov_b32_e32 v44, v2
	v_mov_b32_e32 v45, v2
	v_mov_b32_e32 v50, v2
	v_mov_b32_e32 v51, v2
	v_mov_b32_e32 v52, v2
	v_mov_b32_e32 v53, v2
	v_mov_b32_e32 v58, v2
	v_mov_b32_e32 v59, v2
	v_mov_b32_e32 v60, v2
	v_mov_b32_e32 v61, v2
	v_mov_b32_e32 v6, v2
	v_mov_b32_e32 v7, v2
	v_mov_b32_e32 v8, v2
	v_mov_b32_e32 v9, v2
	v_mov_b32_e32 v14, v2
	v_mov_b32_e32 v15, v2
	v_mov_b32_e32 v16, v2
	v_mov_b32_e32 v17, v2
	v_mov_b32_e32 v22, v2
	v_mov_b32_e32 v23, v2
	v_mov_b32_e32 v24, v2
	v_mov_b32_e32 v25, v2
	v_mov_b32_e32 v30, v2
	v_mov_b32_e32 v31, v2
	v_mov_b32_e32 v32, v2
	v_mov_b32_e32 v33, v2
	v_mov_b32_e32 v38, v2
	v_mov_b32_e32 v39, v2
	v_mov_b32_e32 v40, v2
	v_mov_b32_e32 v41, v2
	v_mov_b32_e32 v46, v2
	v_mov_b32_e32 v47, v2
	v_mov_b32_e32 v48, v2
	v_mov_b32_e32 v49, v2
	v_mov_b32_e32 v54, v2
	v_mov_b32_e32 v55, v2
	v_mov_b32_e32 v56, v2
	v_mov_b32_e32 v57, v2
	v_mov_b32_e32 v62, v2
	v_mov_b32_e32 v63, v2
	v_mov_b32_e32 v64, v2
	v_mov_b32_e32 v65, v2
	v_mov_b32_e32 v66, v2
	v_mov_b32_e32 v67, v2
	v_mov_b32_e32 v68, v2
	v_mov_b32_e32 v69, v2
	v_mov_b32_e32 v74, v2
	v_mov_b32_e32 v75, v2
	v_mov_b32_e32 v76, v2
	v_mov_b32_e32 v77, v2
	v_mov_b32_e32 v90, v2
	v_mov_b32_e32 v91, v2
	v_mov_b32_e32 v92, v2
	v_mov_b32_e32 v93, v2
	v_mov_b32_e32 v106, v2
	v_mov_b32_e32 v107, v2
	v_mov_b32_e32 v108, v2
	v_mov_b32_e32 v109, v2
	v_mov_b32_e32 v114, v2
	v_mov_b32_e32 v115, v2
	v_mov_b32_e32 v116, v2
	v_mov_b32_e32 v117, v2
	v_mov_b32_e32 v122, v2
	v_mov_b32_e32 v123, v2
	v_mov_b32_e32 v124, v2
	v_mov_b32_e32 v125, v2
	v_mov_b32_e32 v130, v2
	v_mov_b32_e32 v131, v2
	v_mov_b32_e32 v132, v2
	v_mov_b32_e32 v133, v2
	v_mov_b32_e32 v142, v2
	v_mov_b32_e32 v143, v2
	v_mov_b32_e32 v144, v2
	v_mov_b32_e32 v145, v2
	v_mov_b32_e32 v70, v2
	v_mov_b32_e32 v71, v2
	v_mov_b32_e32 v72, v2
	v_mov_b32_e32 v73, v2
	v_mov_b32_e32 v78, v2
	v_mov_b32_e32 v79, v2
	v_mov_b32_e32 v80, v2
	v_mov_b32_e32 v81, v2
	v_mov_b32_e32 v94, v2
	v_mov_b32_e32 v95, v2
	v_mov_b32_e32 v96, v2
	v_mov_b32_e32 v97, v2
	v_mov_b32_e32 v110, v2
	v_mov_b32_e32 v111, v2
	v_mov_b32_e32 v112, v2
	v_mov_b32_e32 v113, v2
	v_mov_b32_e32 v118, v2
	v_mov_b32_e32 v119, v2
	v_mov_b32_e32 v120, v2
	v_mov_b32_e32 v121, v2
	v_mov_b32_e32 v126, v2
	v_mov_b32_e32 v127, v2
	v_mov_b32_e32 v128, v2
	v_mov_b32_e32 v129, v2
	v_mov_b32_e32 v134, v2
	v_mov_b32_e32 v135, v2
	v_mov_b32_e32 v136, v2
	v_mov_b32_e32 v137, v2
	v_mov_b32_e32 v138, v2
	v_mov_b32_e32 v139, v2
	v_mov_b32_e32 v140, v2
	v_mov_b32_e32 v141, v2

.LBB0_557:
	s_add_u32 s28, s66, 0x642c000
	s_addc_u32 s29, s67, 0
	s_ashr_i32 s6, s3, 31
	s_lshr_b32 s6, s6, 26
	s_add_i32 s6, s3, s6
	s_lshl_b32 s4, s4, 5
	s_add_i32 m0, s13, 0x18000
	v_lshl_add_u64 v[8:9], v[8:9], 0, s[84:85]
	s_ashr_i32 s30, s6, 6
	s_lshl_b32 s31, s5, 6
	s_lshl_b32 s6, s5, 13
	s_and_b32 s34, s4, 0x60
	s_waitcnt vmcnt(4)
	s_barrier
	global_load_lds_dwordx4 v[8:9], off
	v_lshl_add_u64 v[6:7], v[6:7], 0, s[84:85]
	s_add_i32 m0, s13, 0x1a000
	s_add_i32 s35, s13, 0x8000
	s_add_i32 s38, s13, 0xa000
	global_load_lds_dwordx4 v[6:7], off
	v_lshl_add_u64 v[4:5], v[4:5], 0, s[84:85]
	s_mov_b32 m0, s35
	s_add_u32 s4, s16, 0x40080
	global_load_lds_dwordx4 v[4:5], off
	v_lshl_add_u64 v[2:3], v[2:3], 0, s[84:85]
	s_mov_b32 m0, s38
	s_addc_u32 s5, s17, 0
	global_load_lds_dwordx4 v[2:3], off
	s_add_i32 m0, s13, 0x1c000
	v_lshl_add_u64 v[2:3], s[4:5], 0, v[150:151]
	global_load_lds_dwordx4 v[2:3], off
	v_lshl_add_u64 v[2:3], s[4:5], 0, v[146:147]
	s_add_i32 m0, s13, 0x1e000
	v_and_b32_e32 v4, 1, v14
	global_load_lds_dwordx4 v[2:3], off
	v_lshlrev_b32_e32 v3, 2, v171
	v_lshl_or_b32 v2, v171, 6, v212
	v_and_b32_e32 v3, 32, v3
	v_bitop3_b32 v2, v2, s6, v3 bitop3:0xde
	v_lshlrev_b32_e32 v3, 14, v14
	v_and_b32_e32 v3, 0xffff8000, v3
	v_lshl_add_u32 v3, v13, 11, v3
	v_lshl_or_b32 v3, v4, 6, v3
	v_lshl_add_u32 v154, v15, 1, v3
	v_lshlrev_b32_e32 v3, 14, v10
	v_and_b32_e32 v3, 0xffff8000, v3
	s_waitcnt vmcnt(6)
	v_lshl_add_u32 v3, v11, 11, v3
	v_and_b32_e32 v4, 1, v10
	s_cmp_gt_i32 s3, 63
	v_lshl_or_b32 v3, v4, 6, v3
	s_sext_i32_i16 s42, s2
	v_lshl_or_b32 v159, s34, 7, v213
	s_cselect_b64 s[2:3], -1, 0
	s_add_i32 s39, s30, -2
	s_ashr_i32 s40, s83, 31
	v_mov_b32_e32 v155, v0
	v_lshl_add_u32 v156, v12, 1, v3
	v_mov_b32_e32 v157, v0
	s_mov_b32 s41, 0
	v_add_u32_e32 v173, 0, v2
	s_barrier
	s_waitcnt vmcnt(0)
	s_branch .LBB0_559

.LBB0_618:
	s_add_u32 s0, s66, 0x6040000
	s_addc_u32 s1, s67, 0
	s_add_u32 s28, s66, 0x6416000
	s_addc_u32 s29, s67, 0
	s_ashr_i32 s6, s3, 31
	s_lshr_b32 s6, s6, 26
	s_lshl_b32 s4, s4, 5
	s_add_i32 s6, s3, s6
	s_and_b32 s34, s4, 0x60
	s_add_i32 m0, s13, 0x18000
	v_lshl_add_u64 v[8:9], v[8:9], 0, s[84:85]
	s_ashr_i32 s30, s6, 6
	s_lshl_b32 s31, s5, 6
	s_lshl_b32 s6, s5, 13
	s_lshl_b32 s7, s34, 7
	s_waitcnt vmcnt(4)
	s_barrier
	global_load_lds_dwordx4 v[8:9], off
	v_lshl_add_u64 v[6:7], v[6:7], 0, s[84:85]
	s_add_i32 m0, s13, 0x1a000
	s_add_i32 s35, s13, 0x8000
	s_add_i32 s38, s13, 0xa000
	global_load_lds_dwordx4 v[6:7], off
	v_lshl_add_u64 v[4:5], v[4:5], 0, s[84:85]
	s_mov_b32 m0, s35
	s_add_u32 s4, s16, 0x40080
	global_load_lds_dwordx4 v[4:5], off
	v_lshl_add_u64 v[2:3], v[2:3], 0, s[84:85]
	s_mov_b32 m0, s38
	s_addc_u32 s5, s17, 0
	global_load_lds_dwordx4 v[2:3], off
	s_add_i32 m0, s13, 0x1c000
	v_lshl_add_u64 v[2:3], s[4:5], 0, v[150:151]
	global_load_lds_dwordx4 v[2:3], off
	v_lshl_add_u64 v[2:3], s[4:5], 0, v[146:147]
	s_add_i32 m0, s13, 0x1e000
	v_bfe_u32 v1, v170, 4, 2
	global_load_lds_dwordx4 v[2:3], off
	v_and_b32_e32 v159, 15, v170
	v_lshlrev_b32_e32 v2, 4, v1
	v_lshlrev_b32_e32 v3, 2, v170
	v_lshl_or_b32 v2, v159, 6, v2
	v_and_b32_e32 v3, 32, v3
	v_bitop3_b32 v4, v2, s6, v3 bitop3:0xde
	v_bitop3_b32 v171, s7, v2, v3 bitop3:0xf6
	v_lshlrev_b32_e32 v2, 14, v14
	v_and_b32_e32 v2, 0xffff8000, v2
	v_lshl_add_u32 v2, v13, 11, v2
	v_and_b32_e32 v3, 1, v14
	v_lshl_or_b32 v2, v3, 6, v2
	v_lshl_add_u32 v154, v15, 1, v2
	v_lshlrev_b32_e32 v2, 14, v10
	v_and_b32_e32 v2, 0xffff8000, v2
	s_waitcnt vmcnt(6)
	v_lshl_add_u32 v2, v11, 11, v2
	v_and_b32_e32 v3, 1, v10
	s_cmp_gt_i32 s3, 63
	v_lshl_or_b32 v2, v3, 6, v2
	s_sext_i32_i16 s42, s2
	s_cselect_b64 s[2:3], -1, 0
	s_add_i32 s39, s30, -2
	s_ashr_i32 s40, s83, 31
	v_mov_b32_e32 v155, v0
	v_lshl_add_u32 v156, v12, 1, v2
	v_mov_b32_e32 v157, v0
	s_mov_b32 s41, 0
	v_add_u32_e32 v173, 0, v4
	s_barrier
	s_waitcnt vmcnt(0)
	s_branch .LBB0_620

.LBB0_868:
	s_ashr_i32 s4, s1, 31
	s_lshr_b32 s4, s4, 26
	s_lshl_b32 s2, s2, 5
	s_add_i32 s4, s1, s4
	s_and_b32 s28, s2, 0x60
	s_add_i32 m0, s11, 0x18000
	v_lshl_add_u64 v[8:9], v[8:9], 0, s[84:85]
	s_ashr_i32 s26, s4, 6
	s_lshl_b32 s27, s3, 6
	s_lshl_b32 s4, s3, 13
	s_lshl_b32 s5, s28, 7
	s_waitcnt vmcnt(4)
	s_barrier
	global_load_lds_dwordx4 v[8:9], off
	v_lshl_add_u64 v[6:7], v[6:7], 0, s[84:85]
	s_add_i32 m0, s11, 0x1a000
	s_add_i32 s29, s11, 0x8000
	s_add_i32 s30, s11, 0xa000
	global_load_lds_dwordx4 v[6:7], off
	v_lshl_add_u64 v[4:5], v[4:5], 0, s[84:85]
	s_mov_b32 m0, s29
	s_add_u32 s2, s14, 0x40080
	global_load_lds_dwordx4 v[4:5], off
	v_lshl_add_u64 v[2:3], v[2:3], 0, s[84:85]
	s_mov_b32 m0, s30
	s_addc_u32 s3, s15, 0
	global_load_lds_dwordx4 v[2:3], off
	s_add_i32 m0, s11, 0x1c000
	v_lshl_add_u64 v[2:3], s[2:3], 0, v[150:151]
	global_load_lds_dwordx4 v[2:3], off
	v_lshl_add_u64 v[2:3], s[2:3], 0, v[146:147]
	s_add_i32 m0, s11, 0x1e000
	v_bfe_u32 v1, v170, 4, 2
	global_load_lds_dwordx4 v[2:3], off
	v_and_b32_e32 v159, 15, v170
	v_lshlrev_b32_e32 v2, 4, v1
	v_lshlrev_b32_e32 v3, 2, v170
	v_lshl_or_b32 v2, v159, 6, v2
	v_and_b32_e32 v3, 32, v3
	v_bitop3_b32 v4, v2, s4, v3 bitop3:0xde
	v_bitop3_b32 v171, s5, v2, v3 bitop3:0xf6
	v_lshlrev_b32_e32 v2, 14, v14
	v_and_b32_e32 v2, 0xffff8000, v2
	v_lshl_add_u32 v2, v13, 11, v2
	v_and_b32_e32 v3, 1, v14
	v_lshl_or_b32 v2, v3, 6, v2
	v_lshl_add_u32 v154, v15, 1, v2
	v_lshlrev_b32_e32 v2, 14, v10
	v_and_b32_e32 v2, 0xffff8000, v2
	s_waitcnt vmcnt(6)
	v_lshl_add_u32 v2, v11, 11, v2
	v_and_b32_e32 v3, 1, v10
	s_cmp_gt_i32 s1, 63
	v_lshl_or_b32 v2, v3, 6, v2
	s_sext_i32_i16 s38, s0
	s_cselect_b64 s[0:1], -1, 0
	s_add_i32 s31, s26, -2
	s_ashr_i32 s34, s83, 31
	v_mov_b32_e32 v155, v0
	v_lshl_add_u32 v156, v12, 1, v2
	v_mov_b32_e32 v157, v0
	s_mov_b32 s35, 0
	v_add_u32_e32 v173, 0, v4
	s_barrier
	s_waitcnt vmcnt(0)
	s_branch .LBB0_870

.LBB0_872:
	s_ashr_i32 s5, s4, 31
	s_lshl_b64 s[6:7], s[4:5], 19
	s_add_u32 s6, s64, s6
	s_addc_u32 s7, s65, s7
	s_ashr_i32 s3, s2, 31
	s_lshl_b64 s[8:9], s[2:3], 19
	s_add_u32 s8, s66, s8
	v_mov_b32_e32 v141, 0
	s_addc_u32 s9, s67, s9
	s_andn2_b64 vcc, exec, s[0:1]
	v_mov_b32_e32 v140, v141
	v_mov_b32_e32 v139, v141
	v_mov_b32_e32 v138, v141
	v_mov_b32_e32 v137, v141
	v_mov_b32_e32 v136, v141
	v_mov_b32_e32 v135, v141
	v_mov_b32_e32 v134, v141
	v_mov_b32_e32 v129, v141
	v_mov_b32_e32 v128, v141
	v_mov_b32_e32 v127, v141
	v_mov_b32_e32 v126, v141
	v_mov_b32_e32 v121, v141
	v_mov_b32_e32 v120, v141
	v_mov_b32_e32 v119, v141
	v_mov_b32_e32 v118, v141
	v_mov_b32_e32 v113, v141
	v_mov_b32_e32 v112, v141
	v_mov_b32_e32 v111, v141
	v_mov_b32_e32 v110, v141
	v_mov_b32_e32 v97, v141
	v_mov_b32_e32 v96, v141
	v_mov_b32_e32 v95, v141
	v_mov_b32_e32 v94, v141
	v_mov_b32_e32 v81, v141
	v_mov_b32_e32 v80, v141
	v_mov_b32_e32 v79, v141
	v_mov_b32_e32 v78, v141
	v_mov_b32_e32 v73, v141
	v_mov_b32_e32 v72, v141
	v_mov_b32_e32 v71, v141
	v_mov_b32_e32 v70, v141
	v_mov_b32_e32 v145, v141
	v_mov_b32_e32 v144, v141
	v_mov_b32_e32 v143, v141
	v_mov_b32_e32 v142, v141
	v_mov_b32_e32 v133, v141
	v_mov_b32_e32 v132, v141
	v_mov_b32_e32 v131, v141
	v_mov_b32_e32 v130, v141
	v_mov_b32_e32 v125, v141
	v_mov_b32_e32 v124, v141
	v_mov_b32_e32 v123, v141
	v_mov_b32_e32 v122, v141
	v_mov_b32_e32 v117, v141
	v_mov_b32_e32 v116, v141
	v_mov_b32_e32 v115, v141
	v_mov_b32_e32 v114, v141
	v_mov_b32_e32 v109, v141
	v_mov_b32_e32 v108, v141
	v_mov_b32_e32 v107, v141
	v_mov_b32_e32 v106, v141
	v_mov_b32_e32 v93, v141
	v_mov_b32_e32 v92, v141
	v_mov_b32_e32 v91, v141
	v_mov_b32_e32 v90, v141
	v_mov_b32_e32 v77, v141
	v_mov_b32_e32 v76, v141
	v_mov_b32_e32 v75, v141
	v_mov_b32_e32 v74, v141
	v_mov_b32_e32 v69, v141
	v_mov_b32_e32 v68, v141
	v_mov_b32_e32 v67, v141
	v_mov_b32_e32 v66, v141
	v_mov_b32_e32 v65, v141
	v_mov_b32_e32 v64, v141
	v_mov_b32_e32 v63, v141
	v_mov_b32_e32 v62, v141
	v_mov_b32_e32 v57, v141
	v_mov_b32_e32 v56, v141
	v_mov_b32_e32 v55, v141
	v_mov_b32_e32 v54, v141
	v_mov_b32_e32 v49, v141
	v_mov_b32_e32 v48, v141
	v_mov_b32_e32 v47, v141
	v_mov_b32_e32 v46, v141
	v_mov_b32_e32 v41, v141
	v_mov_b32_e32 v40, v141
	v_mov_b32_e32 v39, v141
	v_mov_b32_e32 v38, v141
	v_mov_b32_e32 v33, v141
	v_mov_b32_e32 v32, v141
	v_mov_b32_e32 v31, v141
	v_mov_b32_e32 v30, v141
	v_mov_b32_e32 v25, v141
	v_mov_b32_e32 v24, v141
	v_mov_b32_e32 v23, v141
	v_mov_b32_e32 v22, v141
	v_mov_b32_e32 v17, v141
	v_mov_b32_e32 v16, v141
	v_mov_b32_e32 v15, v141
	v_mov_b32_e32 v14, v141
	v_mov_b32_e32 v9, v141
	v_mov_b32_e32 v8, v141
	v_mov_b32_e32 v7, v141
	v_mov_b32_e32 v6, v141
	v_mov_b32_e32 v61, v141
	v_mov_b32_e32 v60, v141
	v_mov_b32_e32 v59, v141
	v_mov_b32_e32 v58, v141
	v_mov_b32_e32 v53, v141
	v_mov_b32_e32 v52, v141
	v_mov_b32_e32 v51, v141
	v_mov_b32_e32 v50, v141
	v_mov_b32_e32 v45, v141
	v_mov_b32_e32 v44, v141
	v_mov_b32_e32 v43, v141
	v_mov_b32_e32 v42, v141
	v_mov_b32_e32 v37, v141
	v_mov_b32_e32 v36, v141
	v_mov_b32_e32 v35, v141
	v_mov_b32_e32 v34, v141
	v_mov_b32_e32 v29, v141
	v_mov_b32_e32 v28, v141
	v_mov_b32_e32 v27, v141
	v_mov_b32_e32 v26, v141
	v_mov_b32_e32 v21, v141
	v_mov_b32_e32 v20, v141
	v_mov_b32_e32 v19, v141
	v_mov_b32_e32 v18, v141
	v_mov_b32_e32 v13, v141
	v_mov_b32_e32 v12, v141
	v_mov_b32_e32 v11, v141
	v_mov_b32_e32 v10, v141
	v_mov_b32_e32 v5, v141
	v_mov_b32_e32 v4, v141
	v_mov_b32_e32 v3, v141
	v_mov_b32_e32 v2, v141
	s_cbranch_vccnz .LBB0_869
	v_mov_b64_e32 v[2:3], 0xb00
	v_cmp_lt_i64_e32 vcc, s[16:17], v[2:3]
	s_and_b64 s[16:17], vcc, exec
	s_cselect_b32 s3, s7, s13
	s_cselect_b32 s5, s6, s12
	s_cselect_b32 s39, s9, s15
	s_cselect_b32 s40, s8, s14
	s_add_u32 s12, s12, 0x40080
	s_addc_u32 s13, s13, 0
	s_add_u32 s41, s14, 0x100
	v_mov_b32_e32 v2, 0
	s_addc_u32 s42, s15, 0
	s_mov_b32 s14, 0
	v_mov_b32_e32 v3, v2
	v_mov_b32_e32 v4, v2
	v_mov_b32_e32 v5, v2
	v_mov_b32_e32 v10, v2
	v_mov_b32_e32 v11, v2
	v_mov_b32_e32 v12, v2
	v_mov_b32_e32 v13, v2
	v_mov_b32_e32 v18, v2
	v_mov_b32_e32 v19, v2
	v_mov_b32_e32 v20, v2
	v_mov_b32_e32 v21, v2
	v_mov_b32_e32 v26, v2
	v_mov_b32_e32 v27, v2
	v_mov_b32_e32 v28, v2
	v_mov_b32_e32 v29, v2
	v_mov_b32_e32 v34, v2
	v_mov_b32_e32 v35, v2
	v_mov_b32_e32 v36, v2
	v_mov_b32_e32 v37, v2
	v_mov_b32_e32 v42, v2
	v_mov_b32_e32 v43, v2
	v_mov_b32_e32 v44, v2
	v_mov_b32_e32 v45, v2
	v_mov_b32_e32 v50, v2
	v_mov_b32_e32 v51, v2
	v_mov_b32_e32 v52, v2
	v_mov_b32_e32 v53, v2
	v_mov_b32_e32 v58, v2
	v_mov_b32_e32 v59, v2
	v_mov_b32_e32 v60, v2
	v_mov_b32_e32 v61, v2
	v_mov_b32_e32 v6, v2
	v_mov_b32_e32 v7, v2
	v_mov_b32_e32 v8, v2
	v_mov_b32_e32 v9, v2
	v_mov_b32_e32 v14, v2
	v_mov_b32_e32 v15, v2
	v_mov_b32_e32 v16, v2
	v_mov_b32_e32 v17, v2
	v_mov_b32_e32 v22, v2
	v_mov_b32_e32 v23, v2
	v_mov_b32_e32 v24, v2
	v_mov_b32_e32 v25, v2
	v_mov_b32_e32 v30, v2
	v_mov_b32_e32 v31, v2
	v_mov_b32_e32 v32, v2
	v_mov_b32_e32 v33, v2
	v_mov_b32_e32 v38, v2
	v_mov_b32_e32 v39, v2
	v_mov_b32_e32 v40, v2
	v_mov_b32_e32 v41, v2
	v_mov_b32_e32 v46, v2
	v_mov_b32_e32 v47, v2
	v_mov_b32_e32 v48, v2
	v_mov_b32_e32 v49, v2
	v_mov_b32_e32 v54, v2
	v_mov_b32_e32 v55, v2
	v_mov_b32_e32 v56, v2
	v_mov_b32_e32 v57, v2
	v_mov_b32_e32 v62, v2
	v_mov_b32_e32 v63, v2
	v_mov_b32_e32 v64, v2
	v_mov_b32_e32 v65, v2
	v_mov_b32_e32 v66, v2
	v_mov_b32_e32 v67, v2
	v_mov_b32_e32 v68, v2
	v_mov_b32_e32 v69, v2
	v_mov_b32_e32 v74, v2
	v_mov_b32_e32 v75, v2
	v_mov_b32_e32 v76, v2
	v_mov_b32_e32 v77, v2
	v_mov_b32_e32 v90, v2
	v_mov_b32_e32 v91, v2
	v_mov_b32_e32 v92, v2
	v_mov_b32_e32 v93, v2
	v_mov_b32_e32 v106, v2
	v_mov_b32_e32 v107, v2
	v_mov_b32_e32 v108, v2
	v_mov_b32_e32 v109, v2
	v_mov_b32_e32 v114, v2
	v_mov_b32_e32 v115, v2
	v_mov_b32_e32 v116, v2
	v_mov_b32_e32 v117, v2
	v_mov_b32_e32 v122, v2
	v_mov_b32_e32 v123, v2
	v_mov_b32_e32 v124, v2
	v_mov_b32_e32 v125, v2
	v_mov_b32_e32 v130, v2
	v_mov_b32_e32 v131, v2
	v_mov_b32_e32 v132, v2
	v_mov_b32_e32 v133, v2
	v_mov_b32_e32 v142, v2
	v_mov_b32_e32 v143, v2
	v_mov_b32_e32 v144, v2
	v_mov_b32_e32 v145, v2
	v_mov_b32_e32 v70, v2
	v_mov_b32_e32 v71, v2
	v_mov_b32_e32 v72, v2
	v_mov_b32_e32 v73, v2
	v_mov_b32_e32 v78, v2
	v_mov_b32_e32 v79, v2
	v_mov_b32_e32 v80, v2
	v_mov_b32_e32 v81, v2
	v_mov_b32_e32 v94, v2
	v_mov_b32_e32 v95, v2
	v_mov_b32_e32 v96, v2
	v_mov_b32_e32 v97, v2
	v_mov_b32_e32 v110, v2
	v_mov_b32_e32 v111, v2
	v_mov_b32_e32 v112, v2
	v_mov_b32_e32 v113, v2
	v_mov_b32_e32 v118, v2
	v_mov_b32_e32 v119, v2
	v_mov_b32_e32 v120, v2
	v_mov_b32_e32 v121, v2
	v_mov_b32_e32 v126, v2
	v_mov_b32_e32 v127, v2
	v_mov_b32_e32 v128, v2
	v_mov_b32_e32 v129, v2
	v_mov_b32_e32 v134, v2
	v_mov_b32_e32 v135, v2
	v_mov_b32_e32 v136, v2
	v_mov_b32_e32 v137, v2
	v_mov_b32_e32 v138, v2
	v_mov_b32_e32 v139, v2
	v_mov_b32_e32 v140, v2
	v_mov_b32_e32 v141, v2
